# stack on v48: windowed-loop lazy rebase + 24-bit multiply / fused shift for the K/V prefetch address
# speedup vs baseline: 1.0048x; 1.0048x over previous
; #define LAS __attribute__((address_space(3)))
; DI int get_tid() { int t = threadIdx.x; asm volatile("" : "+v"(t)); return t; }
; DI float opaque0() { float z; asm volatile("v_mov_b32 %0, 0" : "=v"(z)); return z; }
; template <bool MASKED> ...
;     const int tid = get_tid(), lane = tid & 63, wave = tid >> 6, l31 = lane & 31, h = lane >> 5;
;     const int ntiles = nlat + nctx;
;     bf16x8 qf[2][4];
; #pragma unroll
;     for (int q = 0; q < 2; ++q) {
;         const bf16_t* qp = Qb + (size_t)(qrow0 + wave * 64 + q * 32 + l31) * ldq + qcol + 8 * h;
; #pragma unroll
;         for (int ks = 0; ks < 4; ++ks) qf[q][ks] = *(const bf16x8*)(qp + 16 * ks);
;     }
;     const int lrow = tid >> 3, lkc = tid & 7;
;     auto tile_off = [&](int i) -> size_t {
;         const int r0 = (i < nlat) ? (lat_row0 + 64 * i) : (ctx_row0 + 64 * (i - nlat));
;         return (size_t)(r0 + lrow) * ldkv + kvcol + lkc * 8;
;     };
;     lchar* const Kbase = lds; lchar* const Vbase = lds + 2 * KV_K;
;     constexpr int VB = 64 * VSTR;
;     const int koff = lrow * KSTR + lkc * 16, voff = lrow * VSTR + lkc * 16;
;     f32x16 o[2][2];
;     { const float z0 = opaque0();
; #pragma unroll
;       for (int q = 0; q < 2; ++q)
; #pragma unroll
;         for (int dt = 0; dt < 2; ++dt)
; #pragma unroll
;             for (int i = 0; i < 16; ++i) o[q][dt][i] = z0; }
;     float m_ref[2] = {0.f, 0.f}, lsum[2] = {0.f, 0.f};
;     const int qw0 = __builtin_amdgcn_readfirstlane(qpos0 + wave * 64);
;     u32x4 rk, rv;
;     {
;         const u32x4 k0 = *(const u32x4*)(Kb + tile_off(0)), v0 = *(const u32x4*)(Vb + tile_off(0));
;         rk = *(const u32x4*)(Kb + tile_off(1)); rv = *(const u32x4*)(Vb + tile_off(1));
;         *(LAS u32x4*)(Kbase + koff) = k0; *(LAS u32x4*)(Vbase + voff) = v0;
;     }
;     __syncthreads();
;     {
;         *(LAS u32x4*)(Kbase + KV_K + koff) = rk; *(LAS u32x4*)(Vbase + VB + voff) = rv;
;         rk = *(const u32x4*)(Kb + tile_off(2)); rv = *(const u32x4*)(Vb + tile_off(2));
; template <int VAR>
; DI void phase_mixer(const Params& p, int l, lchar* lds) {
;     ...
;                 const int gq = id & 3, nb2 = (id >> 2) & 7, kvh_ = (id >> 5) & 3, b2 = id >> 7, hd2 = kvh_ * 4 + gq;
;                 attn_unit2<false>(Q, ldq, hd2 * 64, b2 * T + nb2 * 512, Kb, Vb, ldkv, kvh_ * 64, b2 * T, 64, 0, 0, NLAT + b2 * CL, 4, -1e30f, 0.f, MIX, D, ocol0 + hd2 * 64, lds);
.LBB0_188:
	s_and_b64 vcc, exec, s[0:1]
	s_cbranch_vccz .LBB0_175
	v_readlane_b32 s22, v254, 20
	v_readlane_b32 s23, v254, 21
	s_mov_b64 s[0:1], -1
	s_and_b64 vcc, exec, s[22:23]
	s_cbranch_vccz .LBB0_195
	s_bfe_u32 s26, s31, 0x20005
	s_lshl_b32 s1, s31, 6
	s_ashr_i32 s2, s31, 7
	s_lshl_b32 s0, s26, 8
	s_and_b32 s1, s1, 0xc0
	s_lshl_b32 s22, s31, 7
	s_or_b32 s0, s0, s1
	s_lshl_b32 s1, s2, 12
	s_and_b32 s22, s22, 0xe00
	v_mov_b32_e32 v98, v171
	s_or_b32 s22, s1, s22
	s_lshl_b32 s2, s2, 8
	s_add_i32 s2, s2, 0x10000
	v_and_b32_e32 v0, 0xffffffc0, v98
	v_add_u32_e32 v0, s22, v0
	s_lshl_b32 s22, s0, 1
	v_readlane_b32 s36, v254, 48
	v_bfe_u32 v99, v98, 5, 1
	v_readlane_b32 s37, v254, 49
	s_add_u32 s22, s36, s22
	s_waitcnt vmcnt(0)
	v_and_b32_e32 v32, 31, v98
	s_addc_u32 s23, s37, 0
	v_lshlrev_b32_e32 v128, 4, v99
	v_or_b32_e32 v174, v0, v32
	v_lshl_add_u64 v[0:1], s[22:23], 0, v[128:129]
	v_readlane_b32 s22, v254, 46
	v_readlane_b32 s23, v254, 47
	s_mov_b32 s36, s22
	v_mad_i64_i32 v[2:3], s[22:23], s36, v174, 0
	v_lshl_add_u64 v[2:3], v[2:3], 1, v[0:1]
	v_or_b32_e32 v172, 32, v174
	v_ashrrev_i32_e32 v188, 3, v98
	global_load_dwordx4 v[130:133], v[2:3], off
	global_load_dwordx4 v[134:137], v[2:3], off offset:32
	global_load_dwordx4 v[138:141], v[2:3], off offset:64
	global_load_dwordx4 v[142:145], v[2:3], off offset:96
	v_mad_i64_i32 v[2:3], s[22:23], s36, v172, 0
	v_add_u32_e32 v33, s1, v188
	v_lshl_add_u64 v[0:1], v[2:3], 1, v[0:1]
	v_mad_i64_i32 v[16:17], s[22:23], s30, v33, 0
	v_readlane_b32 s40, v252, 47
	global_load_dwordx4 v[146:149], v[0:1], off
	global_load_dwordx4 v[150:153], v[0:1], off offset:32
	global_load_dwordx4 v[154:157], v[0:1], off offset:64
	global_load_dwordx4 v[158:161], v[0:1], off offset:96
	v_lshlrev_b32_e32 v0, 4, v98
	v_lshlrev_b64 v[20:21], 1, v[16:17]
	v_readlane_b32 s41, v252, 48
	v_readlane_b32 s36, v252, 31
	v_and_b32_e32 v96, 0x70, v0
	s_movk_i32 s27, 0x90
	v_lshl_add_u64 v[16:17], s[40:41], 0, v[20:21]
	v_readlane_b32 s37, v252, 32
	s_lshl_b32 s36, s26, 7
	v_mad_u64_u32 v[176:177], s[22:23], v188, s27, v[96:97]
	v_lshl_add_u64 v[16:17], v[16:17], 0, s[36:37]
	v_mov_b32_e32 v97, v129
	v_lshl_add_u64 v[16:17], v[16:17], 0, v[96:97]
	v_add_u32_e32 v24, 64, v33
	v_mov_b32 v0, 0
	global_load_dwordx4 v[16:19], v[16:17], off
	v_mad_i64_i32 v[24:25], s[22:23], s30, v24, 0
	v_lshlrev_b64 v[28:29], 1, v[24:25]
	v_lshl_add_u64 v[20:21], s[38:39], 0, v[20:21]
	v_lshl_add_u64 v[24:25], s[40:41], 0, v[28:29]
	v_lshl_add_u64 v[20:21], v[20:21], 0, s[36:37]
	v_lshl_add_u64 v[24:25], v[24:25], 0, s[36:37]
	v_lshl_add_u64 v[28:29], s[38:39], 0, v[28:29]
	v_lshl_add_u64 v[20:21], v[20:21], 0, v[96:97]
	v_lshl_add_u64 v[24:25], v[24:25], 0, v[96:97]
	v_lshl_add_u64 v[28:29], v[28:29], 0, s[36:37]
	global_load_dwordx4 v[20:23], v[20:21], off
	v_lshl_add_u64 v[28:29], v[28:29], 0, v[96:97]
	global_load_dwordx4 v[24:27], v[24:25], off
	v_mad_u64_u32 v[178:179], s[22:23], v188, 48, v[176:177]
	global_load_dwordx4 v[28:31], v[28:29], off
	v_and_b32_e32 v80, 63, v98
	v_mul_u32_u24_e32 v179, 0x90, v32
	v_cmp_gt_u32_e32 vcc, 32, v80
	v_lshlrev_b32_e32 v190, 2, v99
	v_mov_b32_e32 v1, v0
	v_mov_b32_e32 v2, v0
	v_mov_b32_e32 v3, v0
	v_mov_b32_e32 v4, v0
	v_mov_b32_e32 v5, v0
	v_mov_b32_e32 v6, v0
	v_mov_b32_e32 v7, v0
	v_mov_b32_e32 v8, v0
	v_mov_b32_e32 v9, v0
	v_mov_b32_e32 v10, v0
	v_mov_b32_e32 v11, v0
	v_mov_b32_e32 v12, v0
	v_mov_b32_e32 v13, v0
	v_mov_b32_e32 v14, v0
	v_mov_b32_e32 v15, v0
	s_add_u32 s26, s40, s36
	v_ashrrev_i32_e32 v175, 31, v174
	v_ashrrev_i32_e32 v173, 31, v172
	s_waitcnt vmcnt(0)
	ds_write_b128 v176, v[16:19]
	v_add_u32_e32 v16, 0x80, v33
	v_mad_i64_i32 v[16:17], s[22:23], s30, v16, 0
	v_lshlrev_b64 v[16:17], 1, v[16:17]
	v_lshl_add_u64 v[18:19], s[40:41], 0, v[16:17]
	v_lshl_add_u64 v[16:17], s[38:39], 0, v[16:17]
	v_lshl_add_u64 v[18:19], v[18:19], 0, s[36:37]
	v_lshl_add_u64 v[16:17], v[16:17], 0, s[36:37]
	v_lshl_add_u64 v[18:19], v[18:19], 0, v[96:97]
	v_lshl_add_u64 v[16:17], v[16:17], 0, v[96:97]
	s_mov_b32 s23, 0xf149f2ca
	ds_write_b128 v178, v[20:23] offset:18432
	s_waitcnt lgkmcnt(0)
	s_barrier
	ds_write_b128 v176, v[24:27] offset:9216
	ds_write_b128 v178, v[28:31] offset:30720
	global_load_dwordx4 v[162:165], v[18:19], off
	global_load_dwordx4 v[166:169], v[16:17], off
	v_mad_u32_u24 v16, v32, s27, v128
	v_or_b32_e32 v17, 32, v80
	v_mul_u32_u24_e32 v189, 0x90, v17
	v_mad_u32_u24 v17, v17, s27, v128
	ds_read_b128 v[82:85], v16
	ds_read_b128 v[86:89], v16 offset:32
	ds_read_b128 v[90:93], v17
	ds_read_b128 v[100:103], v17 offset:32
	ds_read_b128 v[104:107], v16 offset:64
	ds_read_b128 v[108:111], v17 offset:64
	ds_read_b128 v[112:115], v16 offset:96
	ds_read_b128 v[116:119], v17 offset:96
	v_mov_b32 v32, 0
	v_mov_b32 v16, 0
	s_addc_u32 s27, s41, 0
	v_mov_b32_e32 v33, v32
	v_mov_b32_e32 v34, v32
	v_mov_b32_e32 v35, v32
	v_mov_b32_e32 v36, v32
	v_mov_b32_e32 v37, v32
	v_mov_b32_e32 v38, v32
	v_mov_b32_e32 v39, v32
	v_mov_b32_e32 v40, v32
	v_mov_b32_e32 v41, v32
	v_mov_b32_e32 v42, v32
	v_mov_b32_e32 v43, v32
	v_mov_b32_e32 v44, v32
	v_mov_b32_e32 v45, v32
	v_mov_b32_e32 v46, v32
	v_mov_b32_e32 v47, v32
	v_mov_b32_e32 v17, v16
	v_mov_b32_e32 v18, v16
	s_waitcnt lgkmcnt(7)
	v_mfma_f32_32x32x16_bf16 v[64:79], v[82:85], v[130:133], v[32:47]
	v_mov_b32_e32 v19, v16
	v_mov_b32_e32 v20, v16
	v_mov_b32_e32 v21, v16
	v_mov_b32_e32 v22, v16
	v_mov_b32_e32 v23, v16
	v_mov_b32_e32 v24, v16
	v_mov_b32_e32 v25, v16
	s_waitcnt lgkmcnt(5)
; #define LAS __attribute__((address_space(3)))
; DI float shx(float v, int k, int lane) { return __builtin_bit_cast(float, __builtin_amdgcn_ds_bpermute((lane ^ k) << 2, __builtin_bit_cast(int, v))); }
; DI int crow(int i, int h) { return (i & 3) + 8 * (i >> 2) + 4 * h; }
; #define MFMA32(a, b, c) __builtin_amdgcn_mfma_f32_32x32x16_bf16((a), (b), (c), 0, 0, 0)
; DI float opaque0() { float z; asm volatile("v_mov_b32 %0, 0" : "=v"(z)); return z; }
; template <bool FIRST, bool MASKED>
; DI void attn2_step(f32x16 (&o)[2][2], float (&m_ref)[2], float (&lsum)[2], const bf16x8 (&qf)[2][4], const lchar* Kl, const lchar* Vl, int lane, int kp0, int qw0, float m_init, float l0) {
;     ...
;     bf16x8 kf[4][2];
; #pragma unroll
;     for (int ks = 0; ks < 4; ++ks)
; #pragma unroll
;         for (int kt = 0; kt < 2; ++kt) kf[ks][kt] = *(const LAS bf16x8*)(Kl + (32 * kt + l31) * KSTR + ks * 32 + h * 16);
;     f32x16 sc[2][2];
; #pragma unroll
;     for (int q = 0; q < 2; ++q) {
;         const float init = FIRST ? opaque0() : -m_ref[q];
; #pragma unroll
;         for (int kt = 0; kt < 2; ++kt)
; #pragma unroll
;             for (int i = 0; i < 16; ++i) sc[q][kt][i] = init;
; #pragma unroll
;         for (int ks = 0; ks < 4; ++ks)
; #pragma unroll
;             for (int kt = 0; kt < 2; ++kt) sc[q][kt] = MFMA32(kf[ks][kt], qf[q][ks], sc[q][kt]);
;     }
;     if (MASKED && kp0 >= 0 && !(kp0 >= qw0 + 63 - 128 && kp0 + 63 <= qw0 + 128)) {
; #pragma unroll
;         for (int q = 0; q < 2; ++q) {
;             const int qpos = qw0 + q * 32 + l31;
; #pragma unroll
;             for (int kt = 0; kt < 2; ++kt)
; #pragma unroll
;                 for (int i = 0; i < 16; ++i) {
;                     const int diff = qpos - (kp0 + 32 * kt + crow(i, h));
;                     if (diff > 128 || diff < -128) sc[q][kt][i] = -1e30f;
;                 }
;         }
;     }
;     float mx[2];
; #pragma unroll
;     for (int q = 0; q < 2; ++q) {
;         float m = fmaxf(sc[q][0][0], sc[q][1][0]);
; #pragma unroll
;         for (int i = 1; i < 16; ++i) m = fmaxf(m, fmaxf(sc[q][0][i], sc[q][1][i]));
;         mx[q] = fmaxf(m, shx(m, 32, lane));
	v_mfma_f32_32x32x16_bf16 v[32:47], v[90:93], v[130:133], v[32:47]
	v_mov_b32_e32 v26, v16
	v_mov_b32_e32 v27, v16
	v_mov_b32_e32 v28, v16
	v_mov_b32_e32 v29, v16
	v_mov_b32_e32 v30, v16
	v_mov_b32_e32 v31, v16
	v_lshl_add_u64 v[184:185], s[26:27], 0, v[96:97]
	v_mfma_f32_32x32x16_bf16 v[64:79], v[86:89], v[134:137], v[64:79]
	v_writelane_b32 v252, s36, 31
	s_add_u32 s26, s38, s36
	s_addc_u32 s27, s39, 0
	s_mov_b32 s22, 2
	v_writelane_b32 v252, s37, 32
	v_lshl_add_u64 v[186:187], s[26:27], 0, v[96:97]
	s_waitcnt lgkmcnt(4)
	v_mfma_f32_32x32x16_bf16 v[32:47], v[100:103], v[134:137], v[32:47]
	s_waitcnt lgkmcnt(3)
	v_mfma_f32_32x32x16_bf16 v[64:79], v[104:107], v[138:141], v[64:79]
	s_waitcnt lgkmcnt(2)
	v_mfma_f32_32x32x16_bf16 v[32:47], v[108:111], v[138:141], v[32:47]
	v_mfma_f32_32x32x16_bf16 v[48:63], v[82:85], v[146:149], v[16:31]
	v_mfma_f32_32x32x16_bf16 v[16:31], v[90:93], v[146:149], v[16:31]
	s_waitcnt lgkmcnt(1)
	v_mfma_f32_32x32x16_bf16 v[64:79], v[112:115], v[142:145], v[64:79]
	s_waitcnt lgkmcnt(0)
	v_mfma_f32_32x32x16_bf16 v[32:47], v[116:119], v[142:145], v[32:47]
	s_nop 9
	v_max_f32_e32 v82, v65, v65
	v_max_f32_e32 v83, v66, v66
	v_max_f32_e32 v84, v67, v67
	v_mfma_f32_32x32x16_bf16 v[48:63], v[86:89], v[150:153], v[48:63]
	v_max_f32_e32 v81, v33, v33
	v_max_f32_e32 v81, v82, v81
	v_max_f32_e32 v82, v34, v34
	v_max_f32_e32 v82, v83, v82
	v_max_f32_e32 v83, v35, v35
	v_max3_f32 v81, v64, v32, v81
	v_max_f32_e32 v83, v84, v83
	v_mfma_f32_32x32x16_bf16 v[16:31], v[100:103], v[150:153], v[16:31]
	v_max3_f32 v81, v81, v82, v83
	v_max_f32_e32 v82, v36, v36
	v_max_f32_e32 v83, v68, v68
	v_max_f32_e32 v82, v83, v82
	v_max_f32_e32 v83, v37, v37
	v_max_f32_e32 v84, v69, v69
	v_max_f32_e32 v83, v84, v83
	v_mfma_f32_32x32x16_bf16 v[48:63], v[104:107], v[154:157], v[48:63]
	v_max3_f32 v81, v81, v82, v83
	v_max_f32_e32 v82, v38, v38
	v_max_f32_e32 v83, v70, v70
	v_max_f32_e32 v82, v83, v82
	v_max_f32_e32 v83, v39, v39
	v_max_f32_e32 v84, v71, v71
	v_max_f32_e32 v83, v84, v83
	v_mfma_f32_32x32x16_bf16 v[16:31], v[108:111], v[154:157], v[16:31]
	v_max3_f32 v81, v81, v82, v83
	v_max_f32_e32 v82, v40, v40
	v_max_f32_e32 v83, v72, v72
	v_max_f32_e32 v82, v83, v82
	v_max_f32_e32 v83, v41, v41
	v_max_f32_e32 v84, v73, v73
	v_max_f32_e32 v83, v84, v83
	v_max3_f32 v81, v81, v82, v83
	v_max_f32_e32 v82, v42, v42
	v_max_f32_e32 v83, v74, v74
	v_mfma_f32_32x32x16_bf16 v[48:63], v[112:115], v[158:161], v[48:63]
	v_max_f32_e32 v82, v83, v82
	v_max_f32_e32 v83, v43, v43
	v_max_f32_e32 v84, v75, v75
	v_max_f32_e32 v83, v84, v83
	v_max3_f32 v81, v81, v82, v83
	v_max_f32_e32 v82, v44, v44
	v_max_f32_e32 v83, v76, v76
	v_mfma_f32_32x32x16_bf16 v[16:31], v[116:119], v[158:161], v[16:31]
	v_max_f32_e32 v82, v83, v82
	v_max_f32_e32 v83, v45, v45
	v_max_f32_e32 v84, v77, v77
	v_max_f32_e32 v83, v84, v83
	v_max3_f32 v81, v81, v82, v83
	v_max_f32_e32 v82, v46, v46
	v_max_f32_e32 v83, v78, v78
	v_max_f32_e32 v82, v83, v82
	v_max_f32_e32 v83, v47, v47
	v_max_f32_e32 v84, v79, v79
	v_max_f32_e32 v83, v84, v83
	v_max3_f32 v81, v81, v82, v83
	v_max_f32_e32 v83, v17, v17
	v_max_f32_e32 v84, v49, v49
	v_max_f32_e32 v83, v84, v83
	v_max_f32_e32 v84, v18, v18
	v_max_f32_e32 v85, v50, v50
	v_max_f32_e32 v84, v85, v84
	v_max_f32_e32 v85, v19, v19
	v_max_f32_e32 v86, v51, v51
	v_max3_f32 v83, v48, v16, v83
	v_max_f32_e32 v85, v86, v85
	v_max3_f32 v83, v83, v84, v85
	v_max_f32_e32 v84, v20, v20
	v_max_f32_e32 v85, v52, v52
	v_max_f32_e32 v84, v85, v84
	v_max_f32_e32 v85, v21, v21
	v_max_f32_e32 v86, v53, v53
	v_max_f32_e32 v85, v86, v85
	v_max3_f32 v83, v83, v84, v85
	v_max_f32_e32 v84, v22, v22
	v_max_f32_e32 v85, v54, v54
	v_max_f32_e32 v84, v85, v84
	v_max_f32_e32 v85, v23, v23
	v_max_f32_e32 v86, v55, v55
	v_max_f32_e32 v85, v86, v85
	v_max3_f32 v83, v83, v84, v85
	v_max_f32_e32 v84, v24, v24
	v_max_f32_e32 v85, v56, v56
	v_max_f32_e32 v84, v85, v84
	v_max_f32_e32 v85, v25, v25
	v_max_f32_e32 v86, v57, v57
	v_max_f32_e32 v85, v86, v85
	v_max3_f32 v83, v83, v84, v85
	v_max_f32_e32 v84, v26, v26
	v_max_f32_e32 v85, v58, v58
	v_max_f32_e32 v84, v85, v84
	v_max_f32_e32 v85, v27, v27
	v_max_f32_e32 v86, v59, v59
	v_max_f32_e32 v85, v86, v85
	v_max3_f32 v83, v83, v84, v85
	v_max_f32_e32 v84, v28, v28
	v_max_f32_e32 v85, v60, v60
	v_max_f32_e32 v84, v85, v84
	v_max_f32_e32 v85, v29, v29
	v_max_f32_e32 v86, v61, v61
	v_max_f32_e32 v85, v86, v85
	v_max3_f32 v83, v83, v84, v85
	v_max_f32_e32 v84, v30, v30
	v_max_f32_e32 v85, v62, v62
	v_max_f32_e32 v84, v85, v84
	v_max_f32_e32 v85, v31, v31
	v_max_f32_e32 v86, v63, v63
	v_lshlrev_b32_e32 v100, 2, v80
	v_max_f32_e32 v85, v86, v85
	v_xor_b32_e32 v177, 0x80, v100
	v_max3_f32 v83, v83, v84, v85
	ds_bpermute_b32 v82, v177, v81
	ds_bpermute_b32 v84, v177, v83
	s_waitcnt lgkmcnt(1)
	v_max3_f32 v181, v81, v82, s23
	s_waitcnt lgkmcnt(0)
; DI unsigned pack2(float lo, float hi) { f32x2 v = {lo, hi}; bf16x2_t b = __builtin_convertvector(v, bf16x2_t); return __builtin_bit_cast(unsigned, b); }
; DI float fast_exp2(float x) { return __builtin_amdgcn_exp2f(x); }
; template <bool FIRST, bool MASKED>
; DI void attn2_step(f32x16 (&o)[2][2], float (&m_ref)[2], float (&lsum)[2], const bf16x8 (&qf)[2][4], const lchar* Kl, const lchar* Vl, int lane, int kp0, int qw0, float m_init, float l0) {
;     ...
;     if (FIRST) {
; #pragma unroll
;         for (int q = 0; q < 2; ++q) {
;             m_ref[q] = fmaxf(m_init, mx[q]);
;             lsum[q] = (h == 0) ? l0 * fast_exp2(m_init - m_ref[q]) : 0.f;
; #pragma unroll
;             for (int kt = 0; kt < 2; ++kt)
; #pragma unroll
;                 for (int i = 0; i < 16; ++i) sc[q][kt][i] -= m_ref[q];
;         }
;     } else if (__builtin_amdgcn_ballot_w64(fmaxf(mx[0], mx[1]) > ATT_THR) != 0ull) {
; #pragma unroll
;         for (int q = 0; q < 2; ++q) {
;             const float delta = fmaxf(mx[q], 0.f), alpha = fast_exp2(-delta);
; #pragma unroll
;             for (int dt = 0; dt < 2; ++dt)
; #pragma unroll
;                 for (int i = 0; i < 16; ++i) o[q][dt][i] *= alpha;
;             lsum[q] *= alpha;
; #pragma unroll
;             for (int kt = 0; kt < 2; ++kt)
; #pragma unroll
;                 for (int i = 0; i < 16; ++i) sc[q][kt][i] -= delta;
;             m_ref[q] += delta;
;         }
;     }
;     bf16x8 pf[2][4];
; #pragma unroll
;     for (int q = 0; q < 2; ++q) {
;         float ps = 0.f;
; #pragma unroll
;         for (int kt = 0; kt < 2; ++kt)
; #pragma unroll
;             for (int i = 0; i < 16; ++i) { const float pv = fast_exp2(sc[q][kt][i]); sc[q][kt][i] = pv; ps += pv; }
;         lsum[q] += ps;
; #pragma unroll
;         for (int s = 0; s < 4; ++s) {
;             u32x4 w;
;             const int kt = s >> 1, b = 8 * (s & 1);
;             w.x = pack2(sc[q][kt][b + 0], sc[q][kt][b + 1]); w.y = pack2(sc[q][kt][b + 2], sc[q][kt][b + 3]);
;             w.z = pack2(sc[q][kt][b + 4], sc[q][kt][b + 5]); w.w = pack2(sc[q][kt][b + 6], sc[q][kt][b + 7]);
;             pf[q][s] = __builtin_bit_cast(bf16x8, w);
;         }
;     }
;     {
;         const int qq = (lane & 15) >> 2, pp = lane & 3, g16 = (lane >> 4) & 1;
;         const lchar* vb = Vl + (4 * h + qq) * VSTR + (16 * g16 + 4 * pp) * 2;
	v_max3_f32 v180, v83, v84, s23
	v_sub_f32_e32 v64, v64, v181
	v_sub_f32_e32 v48, v48, v180
	v_sub_f32_e32 v65, v65, v181
	v_sub_f32_e32 v92, v49, v180
	v_sub_f32_e32 v108, v16, v180
	v_sub_f32_e32 v110, v17, v180
	v_exp_f32_e32 v17, v64
	v_exp_f32_e32 v16, v48
	v_sub_f32_e32 v66, v66, v181
	v_sub_f32_e32 v50, v50, v180
	v_sub_f32_e32 v112, v18, v180
	v_sub_f32_e32 v114, v19, v180
	v_exp_f32_e32 v19, v65
	v_exp_f32_e32 v18, v92
	v_sub_f32_e32 v67, v67, v181
	v_sub_f32_e32 v93, v51, v180
	v_sub_f32_e32 v115, v20, v180
	v_sub_f32_e32 v116, v21, v180
	v_exp_f32_e32 v21, v66
	v_exp_f32_e32 v20, v50
	v_sub_f32_e32 v68, v68, v181
	v_sub_f32_e32 v76, v76, v181
	v_sub_f32_e32 v77, v77, v181
	v_sub_f32_e32 v52, v52, v180
	v_sub_f32_e32 v117, v22, v180
	v_sub_f32_e32 v118, v23, v180
	v_exp_f32_e32 v23, v67
	v_exp_f32_e32 v22, v93
	v_sub_f32_e32 v69, v69, v181
	v_sub_f32_e32 v87, v41, v181
	v_sub_f32_e32 v88, v43, v181
	v_sub_f32_e32 v94, v53, v180
	v_sub_f32_e32 v119, v24, v180
	v_sub_f32_e32 v120, v25, v180
	v_exp_f32_e32 v25, v68
	v_exp_f32_e32 v41, v76
	v_exp_f32_e32 v43, v77
	v_pk_add_f32 v[76:77], v[16:17], 0 op_sel_hi:[1,0]
	v_exp_f32_e32 v24, v52
	v_sub_f32_e32 v70, v70, v181
	v_sub_f32_e32 v54, v54, v180
	v_sub_f32_e32 v121, v26, v180
	v_sub_f32_e32 v122, v27, v180
	v_exp_f32_e32 v27, v69
	v_pk_add_f32 v[76:77], v[18:19], v[76:77]
	v_exp_f32_e32 v26, v94
	v_sub_f32_e32 v80, 0xf149f2ca, v181
	v_sub_f32_e32 v71, v71, v181
	v_sub_f32_e32 v95, v55, v180
	v_sub_f32_e32 v123, v28, v180
	v_sub_f32_e32 v124, v29, v180
	v_exp_f32_e32 v29, v70
	v_exp_f32_e32 v28, v54
	v_pk_add_f32 v[76:77], v[20:21], v[76:77]
	v_exp_f32_e32 v85, v80
	v_sub_f32_e32 v72, v72, v181
	v_sub_f32_e32 v32, v32, v181
	v_sub_f32_e32 v80, v33, v181
	v_sub_f32_e32 v33, 0xf149f2ca, v180
	v_sub_f32_e32 v56, v56, v180
	v_sub_f32_e32 v125, v30, v180
	v_sub_f32_e32 v126, v31, v180
	v_exp_f32_e32 v31, v71
	v_exp_f32_e32 v30, v95
	v_pk_add_f32 v[76:77], v[22:23], v[76:77]
	v_sub_f32_e32 v73, v73, v181
	v_sub_f32_e32 v34, v34, v181
	v_exp_f32_e32 v84, v33
	v_sub_f32_e32 v101, v57, v180
	v_exp_f32_e32 v33, v72
	v_exp_f32_e32 v49, v32
	v_exp_f32_e32 v32, v56
	v_pk_add_f32 v[76:77], v[24:25], v[76:77]
	v_sub_f32_e32 v74, v74, v181
	v_sub_f32_e32 v81, v35, v181
	v_sub_f32_e32 v36, v36, v181
	v_sub_f32_e32 v58, v58, v180
	v_exp_f32_e32 v35, v73
	v_exp_f32_e32 v53, v34
	v_exp_f32_e32 v34, v101
	v_pk_add_f32 v[76:77], v[26:27], v[76:77]
	v_sub_f32_e32 v75, v75, v181
	v_sub_f32_e32 v82, v37, v181
	v_sub_f32_e32 v38, v38, v181
	v_sub_f32_e32 v102, v59, v180
	v_exp_f32_e32 v37, v74
	v_exp_f32_e32 v57, v36
	v_exp_f32_e32 v36, v58
	v_pk_add_f32 v[76:77], v[28:29], v[76:77]
	v_sub_f32_e32 v86, v39, v181
	v_sub_f32_e32 v40, v40, v181
	v_sub_f32_e32 v60, v60, v180
	v_sub_f32_e32 v104, v61, v180
	v_exp_f32_e32 v39, v75
	v_exp_f32_e32 v61, v38
	v_exp_f32_e32 v38, v102
	v_pk_add_f32 v[76:77], v[30:31], v[76:77]
	v_sub_f32_e32 v42, v42, v181
	v_exp_f32_e32 v69, v40
	v_exp_f32_e32 v40, v60
	v_pk_add_f32 v[76:77], v[32:33], v[76:77]
	v_sub_f32_e32 v78, v78, v181
	v_sub_f32_e32 v44, v44, v181
	v_sub_f32_e32 v62, v62, v180
	v_exp_f32_e32 v103, v42
	v_pk_add_f32 v[76:77], v[34:35], v[76:77]
	v_exp_f32_e32 v42, v104
	v_sub_f32_e32 v79, v79, v181
	v_sub_f32_e32 v89, v45, v181
	v_sub_f32_e32 v46, v46, v181
	v_sub_f32_e32 v106, v63, v180
	v_exp_f32_e32 v45, v78
	v_exp_f32_e32 v107, v44
	v_pk_add_f32 v[76:77], v[36:37], v[76:77]
	v_exp_f32_e32 v44, v62
	v_sub_f32_e32 v90, v47, v181
	v_exp_f32_e32 v47, v79
	v_exp_f32_e32 v111, v46
	v_pk_add_f32 v[76:77], v[38:39], v[76:77]
	v_exp_f32_e32 v46, v106
	v_pk_add_f32 v[76:77], v[40:41], v[76:77]
	v_exp_f32_e32 v48, v108
	v_exp_f32_e32 v51, v80
	v_exp_f32_e32 v50, v110
	v_pk_add_f32 v[76:77], v[42:43], v[76:77]
	v_exp_f32_e32 v52, v112
	v_pk_add_f32 v[76:77], v[44:45], v[76:77]
	v_exp_f32_e32 v55, v81
	v_exp_f32_e32 v54, v114
	v_pk_add_f32 v[76:77], v[46:47], v[76:77]
	v_exp_f32_e32 v56, v115
	v_pk_add_f32 v[76:77], v[48:49], v[76:77]
	v_exp_f32_e32 v59, v82
	v_exp_f32_e32 v58, v116
	v_pk_add_f32 v[76:77], v[50:51], v[76:77]
	v_exp_f32_e32 v60, v117
	v_pk_add_f32 v[76:77], v[52:53], v[76:77]
	v_exp_f32_e32 v63, v86
	v_exp_f32_e32 v62, v118
	v_pk_add_f32 v[76:77], v[54:55], v[76:77]
	v_exp_f32_e32 v68, v119
	v_pk_add_f32 v[76:77], v[56:57], v[76:77]
	v_exp_f32_e32 v71, v87
	v_pk_add_f32 v[76:77], v[58:59], v[76:77]
	v_exp_f32_e32 v70, v120
	v_pk_add_f32 v[76:77], v[60:61], v[76:77]
	v_exp_f32_e32 v102, v121
	v_exp_f32_e32 v105, v88
	v_pk_add_f32 v[76:77], v[62:63], v[76:77]
	v_exp_f32_e32 v104, v122
	v_exp_f32_e32 v106, v123
	v_pk_add_f32 v[76:77], v[68:69], v[76:77]
	v_exp_f32_e32 v109, v89
	v_exp_f32_e32 v108, v124
	v_pk_add_f32 v[76:77], v[70:71], v[76:77]
	v_exp_f32_e32 v110, v125
	v_pk_add_f32 v[76:77], v[102:103], v[76:77]
	v_exp_f32_e32 v113, v90
	v_exp_f32_e32 v112, v126
	v_pk_add_f32 v[76:77], v[104:105], v[76:77]
	v_cvt_pk_bf16_f32 v92, v16, v18
	v_pk_add_f32 v[76:77], v[106:107], v[76:77]
	v_lshrrev_b32_e32 v16, 2, v98
	v_cvt_pk_bf16_f32 v88, v17, v19
	v_pk_add_f32 v[76:77], v[108:109], v[76:77]
	v_and_b32_e32 v17, 16, v98
	v_and_or_b32 v16, v16, 3, v190
	v_pk_mul_f32 v[78:79], v[84:85], 0 op_sel_hi:[1,0]
	v_pk_add_f32 v[76:77], v[110:111], v[76:77]
	v_mul_u32_u24_e32 v16, 0xc0, v16
	v_and_or_b32 v17, v100, 12, v17
	v_cndmask_b32_e32 v79, 0, v79, vcc
	v_cndmask_b32_e32 v78, 0, v78, vcc
	v_pk_add_f32 v[76:77], v[112:113], v[76:77]
	v_lshl_or_b32 v191, v17, 1, v16
	v_cvt_pk_bf16_f32 v72, v49, v51
	v_pk_add_f32 v[182:183], v[78:79], v[76:77]
	v_cvt_pk_bf16_f32 v76, v48, v50
	ds_read_b64_tr_b16 v[48:49], v191 offset:18432
	ds_read_b64_tr_b16 v[50:51], v191 offset:19968
	ds_read_b64_tr_b16 v[98:99], v191 offset:18496
	ds_read_b64_tr_b16 v[100:101], v191 offset:20032
	v_cvt_pk_bf16_f32 v89, v21, v23
	v_cvt_pk_bf16_f32 v90, v25, v27
	v_cvt_pk_bf16_f32 v91, v29, v31
	v_cvt_pk_bf16_f32 v93, v20, v22
	v_cvt_pk_bf16_f32 v94, v24, v26
	v_cvt_pk_bf16_f32 v95, v28, v30
	v_cvt_pk_bf16_f32 v80, v33, v35
	v_cvt_pk_bf16_f32 v81, v37, v39
	v_cvt_pk_bf16_f32 v82, v41, v43
	v_cvt_pk_bf16_f32 v83, v45, v47
	v_cvt_pk_bf16_f32 v84, v32, v34
	v_cvt_pk_bf16_f32 v85, v36, v38
	v_cvt_pk_bf16_f32 v86, v40, v42
	v_cvt_pk_bf16_f32 v87, v44, v46
	s_waitcnt lgkmcnt(2)
; #define LAS __attribute__((address_space(3)))
; DI unsigned pack2(float lo, float hi) { f32x2 v = {lo, hi}; bf16x2_t b = __builtin_convertvector(v, bf16x2_t); return __builtin_bit_cast(unsigned, b); }
; #define MFMA32(a, b, c) __builtin_amdgcn_mfma_f32_32x32x16_bf16((a), (b), (c), 0, 0, 0)
; DI float fast_exp2(float x) { return __builtin_amdgcn_exp2f(x); }
; template <bool FIRST, bool MASKED>
; DI void attn2_step(f32x16 (&o)[2][2], float (&m_ref)[2], float (&lsum)[2], const bf16x8 (&qf)[2][4], const lchar* Kl, const lchar* Vl, int lane, int kp0, int qw0, float m_init, float l0) {
;     ...
;     bf16x8 pf[2][4];
; #pragma unroll
;     for (int q = 0; q < 2; ++q) {
;         float ps = 0.f;
; #pragma unroll
;         for (int kt = 0; kt < 2; ++kt)
; #pragma unroll
;             for (int i = 0; i < 16; ++i) { const float pv = fast_exp2(sc[q][kt][i]); sc[q][kt][i] = pv; ps += pv; }
;         lsum[q] += ps;
; #pragma unroll
;         for (int s = 0; s < 4; ++s) {
;             u32x4 w;
;             const int kt = s >> 1, b = 8 * (s & 1);
;             w.x = pack2(sc[q][kt][b + 0], sc[q][kt][b + 1]); w.y = pack2(sc[q][kt][b + 2], sc[q][kt][b + 3]);
;             w.z = pack2(sc[q][kt][b + 4], sc[q][kt][b + 5]); w.w = pack2(sc[q][kt][b + 6], sc[q][kt][b + 7]);
;             pf[q][s] = __builtin_bit_cast(bf16x8, w);
;         }
;     }
;     {
;         const int qq = (lane & 15) >> 2, pp = lane & 3, g16 = (lane >> 4) & 1;
;         const lchar* vb = Vl + (4 * h + qq) * VSTR + (16 * g16 + 4 * pp) * 2;
; #pragma unroll
;         for (int s = 0; s < 4; ++s)
; #pragma unroll
;             for (int dt = 0; dt < 2; ++dt) {
;                 const s16x4 lo = __builtin_amdgcn_ds_read_tr16_b64_v4i16((LAS s16x4*)(vb + (16 * s) * VSTR + dt * 64));
;                 const s16x4 hi = __builtin_amdgcn_ds_read_tr16_b64_v4i16((LAS s16x4*)(vb + (16 * s + 8) * VSTR + dt * 64));
;                 const bf16x8 vf = __builtin_shufflevector(lo, hi, 0, 1, 2, 3, 4, 5, 6, 7);
; #pragma unroll
;                 for (int q = 0; q < 2; ++q) o[q][dt] = MFMA32(vf, pf[q][s], o[q][dt]);
;             }
;     }
	v_mfma_f32_32x32x16_bf16 v[32:47], v[48:51], v[88:91], v[0:15]
	v_cvt_pk_bf16_f32 v73, v53, v55
	v_cvt_pk_bf16_f32 v74, v57, v59
	v_cvt_pk_bf16_f32 v75, v61, v63
	v_cvt_pk_bf16_f32 v77, v52, v54
	v_cvt_pk_bf16_f32 v78, v56, v58
	v_cvt_pk_bf16_f32 v79, v60, v62
	v_cvt_pk_bf16_f32 v64, v69, v71
	v_mfma_f32_32x32x16_bf16 v[16:31], v[48:51], v[92:95], v[0:15]
	v_cvt_pk_bf16_f32 v65, v103, v105
	v_cvt_pk_bf16_f32 v66, v107, v109
	v_cvt_pk_bf16_f32 v67, v111, v113
	v_cvt_pk_bf16_f32 v68, v68, v70
	v_cvt_pk_bf16_f32 v69, v102, v104
	v_cvt_pk_bf16_f32 v70, v106, v108
	v_cvt_pk_bf16_f32 v71, v110, v112
	s_waitcnt lgkmcnt(0)
	v_mfma_f32_32x32x16_bf16 v[48:63], v[98:101], v[88:91], v[0:15]
	ds_read_b64_tr_b16 v[88:89], v191 offset:21504
	ds_read_b64_tr_b16 v[90:91], v191 offset:23040
	s_waitcnt lgkmcnt(0)
	v_mfma_f32_32x32x16_bf16 v[32:47], v[88:91], v[80:83], v[32:47]
	v_mfma_f32_32x32x16_bf16 v[16:31], v[88:91], v[84:87], v[16:31]
	ds_read_b64_tr_b16 v[88:89], v191 offset:21568
	ds_read_b64_tr_b16 v[90:91], v191 offset:23104
	v_mfma_f32_32x32x16_bf16 v[0:15], v[98:101], v[92:95], v[0:15]
	s_waitcnt lgkmcnt(0)
	v_mfma_f32_32x32x16_bf16 v[48:63], v[88:91], v[80:83], v[48:63]
	ds_read_b64_tr_b16 v[80:81], v191 offset:24576
	ds_read_b64_tr_b16 v[82:83], v191 offset:26112
	v_mfma_f32_32x32x16_bf16 v[0:15], v[88:91], v[84:87], v[0:15]
	s_waitcnt lgkmcnt(0)
	v_mfma_f32_32x32x16_bf16 v[32:47], v[80:83], v[72:75], v[32:47]
	v_mfma_f32_32x32x16_bf16 v[16:31], v[80:83], v[76:79], v[16:31]
	ds_read_b64_tr_b16 v[80:81], v191 offset:24640
	ds_read_b64_tr_b16 v[82:83], v191 offset:26176
	s_waitcnt lgkmcnt(0)
	v_mfma_f32_32x32x16_bf16 v[48:63], v[80:83], v[72:75], v[48:63]
	ds_read_b64_tr_b16 v[72:73], v191 offset:27648
	ds_read_b64_tr_b16 v[74:75], v191 offset:29184
	v_mfma_f32_32x32x16_bf16 v[0:15], v[80:83], v[76:79], v[0:15]
	s_waitcnt lgkmcnt(0)
	v_mfma_f32_32x32x16_bf16 v[32:47], v[72:75], v[64:67], v[32:47]
	v_mfma_f32_32x32x16_bf16 v[16:31], v[72:75], v[68:71], v[16:31]
	ds_read_b64_tr_b16 v[72:73], v191 offset:27712
	ds_read_b64_tr_b16 v[74:75], v191 offset:29248
	s_waitcnt lgkmcnt(0)
	s_barrier
	v_mfma_f32_32x32x16_bf16 v[48:63], v[72:75], v[64:67], v[48:63]
	v_mfma_f32_32x32x16_bf16 v[0:15], v[72:75], v[68:71], v[0:15]
	v_mov_b32_e32 v247, 0
	v_mov_b32_e32 v240, 0
	v_mov_b32_e32 v242, 0
	s_branch .LBB0_192

; #define LAS __attribute__((address_space(3)))
; #define MFMA32(a, b, c) __builtin_amdgcn_mfma_f32_32x32x16_bf16((a), (b), (c), 0, 0, 0)
; DI float opaque0() { float z; asm volatile("v_mov_b32 %0, 0" : "=v"(z)); return z; }
; template <bool FIRST, bool MASKED>
; DI void attn2_step(f32x16 (&o)[2][2], float (&m_ref)[2], float (&lsum)[2], const bf16x8 (&qf)[2][4], const lchar* Kl, const lchar* Vl, int lane, int kp0, int qw0, float m_init, float l0) {
;     ...
;     bf16x8 kf[4][2];
; #pragma unroll
;     for (int ks = 0; ks < 4; ++ks)
; #pragma unroll
;         for (int kt = 0; kt < 2; ++kt) kf[ks][kt] = *(const LAS bf16x8*)(Kl + (32 * kt + l31) * KSTR + ks * 32 + h * 16);
;     f32x16 sc[2][2];
; #pragma unroll
;     for (int q = 0; q < 2; ++q) {
;         const float init = FIRST ? opaque0() : -m_ref[q];
; #pragma unroll
;         for (int kt = 0; kt < 2; ++kt)
; #pragma unroll
;             for (int i = 0; i < 16; ++i) sc[q][kt][i] = init;
; #pragma unroll
;         for (int ks = 0; ks < 4; ++ks)
; #pragma unroll
;             for (int kt = 0; kt < 2; ++kt) sc[q][kt] = MFMA32(kf[ks][kt], qf[q][ks], sc[q][kt]);
;     }
; template <bool MASKED> ...
;     ...
;     for (int it = 1; it < ntiles; ++it) {
;         *(LAS u32x4*)(Kbase + ((it + 1) & 1) * KV_K + koff) = rk; *(LAS u32x4*)(Vbase + ((it + 1) & 1) * VB + voff) = rv;
;         const int i2 = min(it + 2, ntiles - 1);
;         rk = *(const u32x4*)(Kb + tile_off(i2)); rv = *(const u32x4*)(Vb + tile_off(i2));
;         attn2_step<false, MASKED>(o, m_ref, lsum, qf, Kbase + (it & 1) * KV_K, Vbase + (it & 1) * VB, lane, (it < nlat) ? kpos0 + 64 * it : -1, qw0, m_init, l0);
;         __syncthreads();
;     }
.LBB0_192:
	s_and_b32 s26, s22, 1
	s_mul_i32 s27, s26, 0x2400
	s_add_i32 s23, s22, -1
	v_add_u32_e32 v64, s27, v176
	s_mulk_i32 s26, 0x3000
	s_waitcnt vmcnt(1)
	ds_write_b128 v64, v[162:165]
	v_add_u32_e32 v64, s26, v178
	s_min_i32 s26, s23, 0x41
	s_cmp_lt_u32 s23, 62
	s_cselect_b32 s27, 2, 0xffffffc2
	s_cselect_b32 s36, s1, s2
	s_and_b32 s23, s23, 1
	s_mul_i32 s37, s23, 0x2400
	s_waitcnt vmcnt(0)
	ds_write_b128 v64, v[166:169] offset:18432
	v_or_b32_e32 v64, s37, v128
	v_add_u32_e32 v65, v64, v179
	v_add_u32_e32 v64, v64, v189
	ds_read_b128 v[162:165], v65
	ds_read_b128 v[192:195], v65 offset:32
	ds_read_b128 v[208:211], v64
	ds_read_b128 v[212:215], v64 offset:32
	s_add_i32 s27, s27, s26
	v_xor_b32_e32 v80, 0x80000000, v181
	s_lshl_b32 s26, s27, 6
	v_mov_b32_e32 v81, v80
	v_mov_b64_e32 v[82:83], v[80:81]
	v_mov_b64_e32 v[84:85], v[80:81]
	v_mov_b64_e32 v[86:87], v[80:81]
	v_mov_b64_e32 v[88:89], v[80:81]
	v_mov_b64_e32 v[90:91], v[80:81]
	v_mov_b64_e32 v[92:93], v[80:81]
	v_mov_b64_e32 v[94:95], v[80:81]
	ds_read_b128 v[216:219], v65 offset:64
	ds_read_b128 v[220:223], v65 offset:96
	ds_read_b128 v[224:227], v64 offset:64
	ds_read_b128 v[228:231], v64 offset:96
	s_add_i32 s26, s26, s36
	v_xor_b32_e32 v64, 0x80000000, v180
	s_waitcnt lgkmcnt(7)
	v_mfma_f32_32x32x16_bf16 v[112:127], v[162:165], v[130:133], v[80:95]
	v_add_u32_e32 v166, s26, v188
	v_mov_b32_e32 v65, v64
	v_mov_b64_e32 v[66:67], v[64:65]
	v_mov_b64_e32 v[68:69], v[64:65]
	s_waitcnt lgkmcnt(5)
	v_mfma_f32_32x32x16_bf16 v[80:95], v[208:211], v[130:133], v[80:95]
	v_mov_b64_e32 v[70:71], v[64:65]
	v_mov_b64_e32 v[72:73], v[64:65]
	v_mov_b64_e32 v[74:75], v[64:65]
	v_mov_b64_e32 v[76:77], v[64:65]
	v_mov_b64_e32 v[78:79], v[64:65]
	v_mfma_f32_32x32x16_bf16 v[112:127], v[192:195], v[134:137], v[112:127]
	s_nop 0
	v_mfma_f32_32x32x16_bf16 v[96:111], v[162:165], v[146:149], v[64:79]
	v_mul_u32_u24_e32 v246, s30, v166
	v_lshl_add_u64 v[164:165], v[246:247], 1, v[184:185]
	v_lshl_add_u64 v[166:167], v[246:247], 1, v[186:187]
	global_load_dwordx4 v[162:165], v[164:165], off
	s_nop 0
	global_load_dwordx4 v[166:169], v[166:167], off
	s_mov_b32 s26, 0x43800000
	s_waitcnt lgkmcnt(4)
	v_mfma_f32_32x32x16_bf16 v[80:95], v[212:215], v[134:137], v[80:95]
	s_waitcnt lgkmcnt(3)
	v_mfma_f32_32x32x16_bf16 v[112:127], v[216:219], v[138:141], v[112:127]
	s_waitcnt lgkmcnt(1)
	v_mfma_f32_32x32x16_bf16 v[80:95], v[224:227], v[138:141], v[80:95]
	v_mfma_f32_32x32x16_bf16 v[64:79], v[208:211], v[146:149], v[64:79]
	v_mfma_f32_32x32x16_bf16 v[112:127], v[220:223], v[142:145], v[112:127]
	s_waitcnt lgkmcnt(0)
	v_mfma_f32_32x32x16_bf16 v[80:95], v[228:231], v[142:145], v[80:95]
	v_mfma_f32_32x32x16_bf16 v[96:111], v[192:195], v[150:153], v[96:111]
	v_mfma_f32_32x32x16_bf16 v[64:79], v[212:215], v[150:153], v[64:79]
	v_mfma_f32_32x32x16_bf16 v[96:111], v[216:219], v[154:157], v[96:111]
	v_mfma_f32_32x32x16_bf16 v[64:79], v[224:227], v[154:157], v[64:79]
	v_mfma_f32_32x32x16_bf16 v[96:111], v[220:223], v[158:161], v[96:111]
	v_mfma_f32_32x32x16_bf16 v[64:79], v[228:231], v[158:161], v[64:79]
	s_mulk_i32 s23, 0x3000
	v_or_b32_e32 v244, s23, v191
	ds_read_b64_tr_b16 v[208:209], v244 offset:18432
	ds_read_b64_tr_b16 v[210:211], v244 offset:19968
	ds_read_b64_tr_b16 v[212:213], v244 offset:18496
	ds_read_b64_tr_b16 v[214:215], v244 offset:20032
	ds_read_b64_tr_b16 v[216:217], v244 offset:21504
	ds_read_b64_tr_b16 v[218:219], v244 offset:23040
	ds_read_b64_tr_b16 v[220:221], v244 offset:21568
	ds_read_b64_tr_b16 v[222:223], v244 offset:23104
	s_waitcnt lgkmcnt(0)
	ds_read_b64_tr_b16 v[224:225], v244 offset:24576
	ds_read_b64_tr_b16 v[226:227], v244 offset:26112
	ds_read_b64_tr_b16 v[228:229], v244 offset:24640
	ds_read_b64_tr_b16 v[230:231], v244 offset:26176
	ds_read_b64_tr_b16 v[232:233], v244 offset:27648
	ds_read_b64_tr_b16 v[234:235], v244 offset:29184
	ds_read_b64_tr_b16 v[236:237], v244 offset:27712
	ds_read_b64_tr_b16 v[238:239], v244 offset:29248
	v_max_f32_e32 v194, v240, v242
	v_cmp_lt_f32_e32 vcc, s26, v194
	s_cbranch_vccz .LBB0_191
; DI float fast_exp2(float x) { return __builtin_amdgcn_exp2f(x); }
; template <bool FIRST, bool MASKED>
; DI void attn2_step(f32x16 (&o)[2][2], float (&m_ref)[2], float (&lsum)[2], const bf16x8 (&qf)[2][4], const lchar* Kl, const lchar* Vl, int lane, int kp0, int qw0, float m_init, float l0) {
;     ...
;     } else if (__builtin_amdgcn_ballot_w64(fmaxf(mx[0], mx[1]) > ATT_THR) != 0ull) {
; #pragma unroll
;         for (int q = 0; q < 2; ++q) {
;             const float delta = fmaxf(mx[q], 0.f), alpha = fast_exp2(-delta);
; #pragma unroll
;             for (int dt = 0; dt < 2; ++dt)
; #pragma unroll
;                 for (int i = 0; i < 16; ++i) o[q][dt][i] *= alpha;
;             lsum[q] *= alpha;
; #pragma unroll
;             for (int kt = 0; kt < 2; ++kt)
; #pragma unroll
;                 for (int i = 0; i < 16; ++i) sc[q][kt][i] -= delta;
;             m_ref[q] += delta;
;         }
;     }
	s_nop 15
	v_log_f32_e32 v193, v240
	v_log_f32_e32 v192, v242
	s_nop 1
	v_mov_b32_e32 v194, v193
	v_mov_b32_e32 v195, v192
	s_nop 1
	v_permlane32_swap_b32_e32 v194, v193
	v_permlane32_swap_b32_e32 v195, v192
	s_nop 1
	v_max_f32_e32 v193, v193, v194
	v_max_f32_e32 v192, v192, v195
	v_max_f32_e32 v193, v193, v193
	v_max_f32_e32 v192, v192, v192
	v_max_f32_e32 v194, 0, v193
	v_max_f32_e32 v192, 0, v192
	v_exp_f32_e64 v196, -v194
	v_exp_f32_e64 v200, -v192
	v_pk_add_f32 v[96:97], v[96:97], v[192:193] op_sel_hi:[1,0] neg_lo:[0,1] neg_hi:[0,1]
	v_pk_add_f32 v[98:99], v[98:99], v[192:193] op_sel_hi:[1,0] neg_lo:[0,1] neg_hi:[0,1]
	v_pk_add_f32 v[100:101], v[100:101], v[192:193] op_sel_hi:[1,0] neg_lo:[0,1] neg_hi:[0,1]
	v_pk_mul_f32 v[30:31], v[30:31], v[200:201] op_sel_hi:[1,0]
	v_pk_mul_f32 v[28:29], v[28:29], v[200:201] op_sel_hi:[1,0]
	v_pk_mul_f32 v[26:27], v[26:27], v[200:201] op_sel_hi:[1,0]
	v_pk_mul_f32 v[24:25], v[24:25], v[200:201] op_sel_hi:[1,0]
	v_pk_mul_f32 v[22:23], v[22:23], v[200:201] op_sel_hi:[1,0]
	v_pk_mul_f32 v[20:21], v[20:21], v[200:201] op_sel_hi:[1,0]
	v_pk_mul_f32 v[18:19], v[18:19], v[200:201] op_sel_hi:[1,0]
	v_pk_mul_f32 v[16:17], v[16:17], v[200:201] op_sel_hi:[1,0]
	v_pk_mul_f32 v[14:15], v[14:15], v[200:201] op_sel_hi:[1,0]
	v_pk_mul_f32 v[12:13], v[12:13], v[200:201] op_sel_hi:[1,0]
	v_pk_mul_f32 v[10:11], v[10:11], v[200:201] op_sel_hi:[1,0]
	v_pk_mul_f32 v[8:9], v[8:9], v[200:201] op_sel_hi:[1,0]
	v_pk_mul_f32 v[6:7], v[6:7], v[200:201] op_sel_hi:[1,0]
	v_pk_mul_f32 v[4:5], v[4:5], v[200:201] op_sel_hi:[1,0]
	v_pk_mul_f32 v[2:3], v[2:3], v[200:201] op_sel_hi:[1,0]
	v_pk_mul_f32 v[0:1], v[0:1], v[200:201] op_sel_hi:[1,0]
	v_mov_b32_e32 v201, v196
	v_pk_add_f32 v[102:103], v[102:103], v[192:193] op_sel_hi:[1,0] neg_lo:[0,1] neg_hi:[0,1]
	v_pk_add_f32 v[104:105], v[104:105], v[192:193] op_sel_hi:[1,0] neg_lo:[0,1] neg_hi:[0,1]
	v_pk_add_f32 v[106:107], v[106:107], v[192:193] op_sel_hi:[1,0] neg_lo:[0,1] neg_hi:[0,1]
	v_pk_add_f32 v[108:109], v[108:109], v[192:193] op_sel_hi:[1,0] neg_lo:[0,1] neg_hi:[0,1]
	v_pk_add_f32 v[110:111], v[110:111], v[192:193] op_sel_hi:[1,0] neg_lo:[0,1] neg_hi:[0,1]
	v_pk_add_f32 v[64:65], v[64:65], v[192:193] op_sel_hi:[1,0] neg_lo:[0,1] neg_hi:[0,1]
	v_pk_add_f32 v[66:67], v[66:67], v[192:193] op_sel_hi:[1,0] neg_lo:[0,1] neg_hi:[0,1]
	v_pk_add_f32 v[68:69], v[68:69], v[192:193] op_sel_hi:[1,0] neg_lo:[0,1] neg_hi:[0,1]
	v_pk_add_f32 v[70:71], v[70:71], v[192:193] op_sel_hi:[1,0] neg_lo:[0,1] neg_hi:[0,1]
	v_pk_add_f32 v[72:73], v[72:73], v[192:193] op_sel_hi:[1,0] neg_lo:[0,1] neg_hi:[0,1]
	v_pk_add_f32 v[74:75], v[74:75], v[192:193] op_sel_hi:[1,0] neg_lo:[0,1] neg_hi:[0,1]
	v_pk_add_f32 v[76:77], v[76:77], v[192:193] op_sel_hi:[1,0] neg_lo:[0,1] neg_hi:[0,1]
	v_pk_add_f32 v[78:79], v[78:79], v[192:193] op_sel_hi:[1,0] neg_lo:[0,1] neg_hi:[0,1]
	v_mov_b32_e32 v193, v194
	v_pk_mul_f32 v[46:47], v[46:47], v[196:197] op_sel_hi:[1,0]
	v_pk_mul_f32 v[44:45], v[44:45], v[196:197] op_sel_hi:[1,0]
	v_pk_mul_f32 v[42:43], v[42:43], v[196:197] op_sel_hi:[1,0]
	v_pk_mul_f32 v[40:41], v[40:41], v[196:197] op_sel_hi:[1,0]
	v_pk_mul_f32 v[38:39], v[38:39], v[196:197] op_sel_hi:[1,0]
	v_pk_mul_f32 v[36:37], v[36:37], v[196:197] op_sel_hi:[1,0]
	v_pk_mul_f32 v[34:35], v[34:35], v[196:197] op_sel_hi:[1,0]
	v_pk_mul_f32 v[32:33], v[32:33], v[196:197] op_sel_hi:[1,0]
	v_pk_mul_f32 v[62:63], v[62:63], v[196:197] op_sel_hi:[1,0]
	v_pk_mul_f32 v[60:61], v[60:61], v[196:197] op_sel_hi:[1,0]
	v_pk_mul_f32 v[58:59], v[58:59], v[196:197] op_sel_hi:[1,0]
	v_pk_mul_f32 v[56:57], v[56:57], v[196:197] op_sel_hi:[1,0]
	v_pk_mul_f32 v[54:55], v[54:55], v[196:197] op_sel_hi:[1,0]
	v_pk_mul_f32 v[52:53], v[52:53], v[196:197] op_sel_hi:[1,0]
	v_pk_mul_f32 v[50:51], v[50:51], v[196:197] op_sel_hi:[1,0]
	v_pk_mul_f32 v[48:49], v[48:49], v[196:197] op_sel_hi:[1,0]
	v_pk_add_f32 v[112:113], v[112:113], v[194:195] op_sel_hi:[1,0] neg_lo:[0,1] neg_hi:[0,1]
	v_pk_add_f32 v[114:115], v[114:115], v[194:195] op_sel_hi:[1,0] neg_lo:[0,1] neg_hi:[0,1]
	v_pk_add_f32 v[116:117], v[116:117], v[194:195] op_sel_hi:[1,0] neg_lo:[0,1] neg_hi:[0,1]
	v_pk_add_f32 v[118:119], v[118:119], v[194:195] op_sel_hi:[1,0] neg_lo:[0,1] neg_hi:[0,1]
	v_pk_add_f32 v[120:121], v[120:121], v[194:195] op_sel_hi:[1,0] neg_lo:[0,1] neg_hi:[0,1]
	v_pk_add_f32 v[122:123], v[122:123], v[194:195] op_sel_hi:[1,0] neg_lo:[0,1] neg_hi:[0,1]
	v_pk_add_f32 v[124:125], v[124:125], v[194:195] op_sel_hi:[1,0] neg_lo:[0,1] neg_hi:[0,1]
	v_pk_add_f32 v[126:127], v[126:127], v[194:195] op_sel_hi:[1,0] neg_lo:[0,1] neg_hi:[0,1]
	v_pk_add_f32 v[80:81], v[80:81], v[194:195] op_sel_hi:[1,0] neg_lo:[0,1] neg_hi:[0,1]
	v_pk_add_f32 v[82:83], v[82:83], v[194:195] op_sel_hi:[1,0] neg_lo:[0,1] neg_hi:[0,1]
	v_pk_add_f32 v[84:85], v[84:85], v[194:195] op_sel_hi:[1,0] neg_lo:[0,1] neg_hi:[0,1]
	v_pk_add_f32 v[86:87], v[86:87], v[194:195] op_sel_hi:[1,0] neg_lo:[0,1] neg_hi:[0,1]
	v_pk_add_f32 v[88:89], v[88:89], v[194:195] op_sel_hi:[1,0] neg_lo:[0,1] neg_hi:[0,1]
	v_pk_add_f32 v[90:91], v[90:91], v[194:195] op_sel_hi:[1,0] neg_lo:[0,1] neg_hi:[0,1]
	v_pk_add_f32 v[92:93], v[92:93], v[194:195] op_sel_hi:[1,0] neg_lo:[0,1] neg_hi:[0,1]
	v_pk_add_f32 v[94:95], v[94:95], v[194:195] op_sel_hi:[1,0] neg_lo:[0,1] neg_hi:[0,1]
	v_pk_mul_f32 v[182:183], v[182:183], v[200:201]
	v_pk_add_f32 v[180:181], v[180:181], v[192:193]
	s_branch .LBB0_191
